# v15 + P0 weight-transpose inner loop fully unrolled: 32 loads in flight per wave instead of 16 (counted vmcnt 31..0)
# speedup vs baseline: 1.0051x; 1.0019x over previous
; __device__ __forceinline__ void p0_transpose_item(const float* W, int N, bf16_t* WT, int ldt, int k0, int n0, int nrow0, int kcol0, LAS float* scr, int lane) {
; #pragma unroll 8
;     for (int i = 0; i < 32; ++i) { const int kk = 2 * i + (lane >> 5); scr[kk * 33 + (lane & 31)] = W[(size_t)(k0 + kk) * N + n0 + (lane & 31)]; }
.LBB0_30:
	s_lshl_b32 s18, s17, 1
	s_lshl_b32 s19, s15, 1
	v_or_b32_e32 v50, s18, v1
	v_or_b32_e32 v51, s19, v2
	s_add_i32 s20, s18, 4
	s_add_i32 s21, s19, 4
	s_add_i32 s22, s18, 8
	s_add_i32 s23, s19, 8
	s_add_i32 s24, s18, 12
	s_add_i32 s25, s19, 12
	s_add_i32 s26, s18, 16
	s_add_i32 s27, s19, 16
	s_add_i32 s28, s18, 20
	s_add_i32 s29, s19, 20
	s_add_i32 s30, s18, 24
	s_add_i32 s31, s19, 24
	s_add_i32 s18, s18, 28
	s_add_i32 s19, s19, 28
	v_add_u32_e32 v18, s6, v51
	v_or_b32_e32 v52, s20, v1
	v_or_b32_e32 v53, s21, v2
	v_or_b32_e32 v54, s22, v1
	v_or_b32_e32 v55, s23, v2
	v_or_b32_e32 v56, s24, v1
	v_or_b32_e32 v57, s25, v2
	v_or_b32_e32 v58, s26, v1
	v_or_b32_e32 v59, s27, v2
	v_or_b32_e32 v60, s28, v1
	v_or_b32_e32 v61, s29, v2
	v_or_b32_e32 v62, s30, v1
	v_or_b32_e32 v63, s31, v2
	v_or_b32_e32 v64, s18, v1
	v_or_b32_e32 v65, s19, v2
	v_add_u32_e32 v20, s9, v50
	v_mad_i64_i32 v[18:19], s[18:19], v18, s14, v[10:11]
	v_add_u32_e32 v24, s9, v52
	v_add_u32_e32 v22, s6, v53
	v_add_u32_e32 v28, s9, v54
	v_add_u32_e32 v26, s6, v55
	v_add_u32_e32 v32, s9, v56
	v_add_u32_e32 v30, s6, v57
	v_add_u32_e32 v36, s9, v58
	v_add_u32_e32 v34, s6, v59
	v_add_u32_e32 v40, s9, v60
	v_add_u32_e32 v38, s6, v61
	v_add_u32_e32 v44, s9, v62
	v_add_u32_e32 v42, s6, v63
	v_add_u32_e32 v48, s9, v64
	v_add_u32_e32 v46, s6, v65
	v_mad_i64_i32 v[20:21], s[18:19], v20, s14, v[10:11]
	v_mad_i64_i32 v[22:23], s[18:19], v22, s14, v[10:11]
	v_mad_i64_i32 v[24:25], s[18:19], v24, s14, v[10:11]
	v_mad_i64_i32 v[26:27], s[18:19], v26, s14, v[10:11]
	v_mad_i64_i32 v[28:29], s[18:19], v28, s14, v[10:11]
	v_mad_i64_i32 v[30:31], s[18:19], v30, s14, v[10:11]
	v_mad_i64_i32 v[32:33], s[18:19], v32, s14, v[10:11]
	v_mad_i64_i32 v[34:35], s[18:19], v34, s14, v[10:11]
	v_mad_i64_i32 v[36:37], s[18:19], v36, s14, v[10:11]
	v_mad_i64_i32 v[38:39], s[18:19], v38, s14, v[10:11]
	v_mad_i64_i32 v[40:41], s[18:19], v40, s14, v[10:11]
	v_mad_i64_i32 v[42:43], s[18:19], v42, s14, v[10:11]
	v_mad_i64_i32 v[44:45], s[18:19], v44, s14, v[10:11]
	v_mad_i64_i32 v[46:47], s[18:19], v46, s14, v[10:11]
	v_mad_i64_i32 v[48:49], s[18:19], v48, s14, v[10:11]
	global_load_dword v66, v[18:19], off
	global_load_dword v67, v[20:21], off
	global_load_dword v68, v[22:23], off
	global_load_dword v69, v[24:25], off
	global_load_dword v70, v[26:27], off
	global_load_dword v71, v[28:29], off
	global_load_dword v72, v[30:31], off
	global_load_dword v73, v[32:33], off
	global_load_dword v74, v[34:35], off
	global_load_dword v75, v[36:37], off
	global_load_dword v76, v[38:39], off
	global_load_dword v77, v[40:41], off
	global_load_dword v78, v[42:43], off
	global_load_dword v79, v[44:45], off
	global_load_dword v80, v[46:47], off
	global_load_dword v81, v[48:49], off
	s_add_i32 s15, s15, 16
	s_add_i32 s17, s17, 16
	s_add_i32 s16, s16, -16
	v_mad_u64_u32 v[18:19], s[18:19], v51, s13, v[4:5]
	s_cmp_lg_u32 s16, 0
	v_mad_u64_u32 v[20:21], s[18:19], v50, s13, v[4:5]
	v_mad_u64_u32 v[22:23], s[18:19], v53, s13, v[4:5]
	v_mad_u64_u32 v[24:25], s[18:19], v52, s13, v[4:5]
	v_mad_u64_u32 v[26:27], s[18:19], v55, s13, v[4:5]
	v_mad_u64_u32 v[28:29], s[18:19], v54, s13, v[4:5]
	v_mad_u64_u32 v[30:31], s[18:19], v57, s13, v[4:5]
	v_mad_u64_u32 v[32:33], s[18:19], v56, s13, v[4:5]
	v_mad_u64_u32 v[34:35], s[18:19], v59, s13, v[4:5]
	v_mad_u64_u32 v[36:37], s[18:19], v58, s13, v[4:5]
	v_mad_u64_u32 v[38:39], s[18:19], v61, s13, v[4:5]
	v_mad_u64_u32 v[40:41], s[18:19], v60, s13, v[4:5]
	v_mad_u64_u32 v[42:43], s[18:19], v63, s13, v[4:5]
	v_mad_u64_u32 v[44:45], s[18:19], v62, s13, v[4:5]
	v_mad_u64_u32 v[46:47], s[18:19], v65, s13, v[4:5]
	v_mad_u64_u32 v[48:49], s[18:19], v64, s13, v[4:5]
	s_nop 7
	s_lshl_b32 s18, s17, 1
	s_lshl_b32 s19, s15, 1
	v_or_b32_e32 v172, s18, v1
	v_or_b32_e32 v173, s19, v2
	s_add_i32 s20, s18, 4
	s_add_i32 s21, s19, 4
	s_add_i32 s22, s18, 8
	s_add_i32 s23, s19, 8
	s_add_i32 s24, s18, 12
	s_add_i32 s25, s19, 12
	s_add_i32 s26, s18, 16
	s_add_i32 s27, s19, 16
	s_add_i32 s28, s18, 20
	s_add_i32 s29, s19, 20
	s_add_i32 s30, s18, 24
	s_add_i32 s31, s19, 24
	s_add_i32 s18, s18, 28
	s_add_i32 s19, s19, 28
	v_add_u32_e32 v140, s6, v173
	v_or_b32_e32 v174, s20, v1
	v_or_b32_e32 v175, s21, v2
	v_or_b32_e32 v176, s22, v1
	v_or_b32_e32 v177, s23, v2
	v_or_b32_e32 v178, s24, v1
	v_or_b32_e32 v179, s25, v2
	v_or_b32_e32 v180, s26, v1
	v_or_b32_e32 v181, s27, v2
	v_or_b32_e32 v182, s28, v1
	v_or_b32_e32 v183, s29, v2
	v_or_b32_e32 v184, s30, v1
	v_or_b32_e32 v185, s31, v2
	v_or_b32_e32 v186, s18, v1
	v_or_b32_e32 v187, s19, v2
	v_add_u32_e32 v142, s9, v172
	v_mad_i64_i32 v[140:141], s[18:19], v140, s14, v[10:11]
	v_add_u32_e32 v146, s9, v174
	v_add_u32_e32 v144, s6, v175
	v_add_u32_e32 v150, s9, v176
	v_add_u32_e32 v148, s6, v177
	v_add_u32_e32 v154, s9, v178
	v_add_u32_e32 v152, s6, v179
	v_add_u32_e32 v158, s9, v180
	v_add_u32_e32 v156, s6, v181
	v_add_u32_e32 v162, s9, v182
	v_add_u32_e32 v160, s6, v183
	v_add_u32_e32 v166, s9, v184
	v_add_u32_e32 v164, s6, v185
	v_add_u32_e32 v170, s9, v186
	v_add_u32_e32 v168, s6, v187
	v_mad_i64_i32 v[142:143], s[18:19], v142, s14, v[10:11]
	v_mad_i64_i32 v[144:145], s[18:19], v144, s14, v[10:11]
	v_mad_i64_i32 v[146:147], s[18:19], v146, s14, v[10:11]
	v_mad_i64_i32 v[148:149], s[18:19], v148, s14, v[10:11]
	v_mad_i64_i32 v[150:151], s[18:19], v150, s14, v[10:11]
	v_mad_i64_i32 v[152:153], s[18:19], v152, s14, v[10:11]
	v_mad_i64_i32 v[154:155], s[18:19], v154, s14, v[10:11]
	v_mad_i64_i32 v[156:157], s[18:19], v156, s14, v[10:11]
	v_mad_i64_i32 v[158:159], s[18:19], v158, s14, v[10:11]
	v_mad_i64_i32 v[160:161], s[18:19], v160, s14, v[10:11]
; #define LAS __attribute__((address_space(3)))
; __device__ __forceinline__ unsigned cvt_pk_bf16(float lo, float hi) { unsigned r; asm volatile("v_cvt_pk_bf16_f32 %0, %1, %2" : "=v"(r) : "v"(lo), "v"(hi)); return r; }
; #define LDS_WAIT() asm volatile("s_waitcnt lgkmcnt(0)" ::: "memory")
; __device__ __forceinline__ void p0_transpose_item(const float* W, int N, bf16_t* WT, int ldt, int k0, int n0, int nrow0, int kcol0, LAS float* scr, int lane) {
; #pragma unroll 8
;     for (int i = 0; i < 32; ++i) { const int kk = 2 * i + (lane >> 5); scr[kk * 33 + (lane & 31)] = W[(size_t)(k0 + kk) * N + n0 + (lane & 31)]; }
;     LDS_WAIT(); asm volatile("" ::: "memory");
;     const int c = lane & 7;
; #pragma unroll
;     for (int j = 0; j < 4; ++j) { const int n = (lane >> 3) + 8 * j; const LAS float* s = scr + (8 * c) * 33 + n;
;         u32x4 o; o.x = cvt_pk_bf16(s[0 * 33], s[1 * 33]); o.y = cvt_pk_bf16(s[2 * 33], s[3 * 33]); o.z = cvt_pk_bf16(s[4 * 33], s[5 * 33]); o.w = cvt_pk_bf16(s[6 * 33], s[7 * 33]);
;         *(u32x4*)(WT + (size_t)(nrow0 + n) * ldt + kcol0 + k0 + 8 * c) = o; }
;     LDS_WAIT(); asm volatile("" ::: "memory");
; }
; __device__ __forceinline__ void p0_prologue(const Frame& F) {
;     ...
;                 for (int it = first; it < nitems; it += NGW) { const int kb = it / nblk, nbk = it % nblk, n0 = nbk * 32;
;                     const int nrow0 = (jb == 0 && n0 >= 3392) ? n0 + 192 : n0;
;                     p0_transpose_item(W, J.N, WT, J.ldt, kb * 64, n0, nrow0, J.kcol0, scr, F.lane); }
	v_mad_i64_i32 v[162:163], s[18:19], v162, s14, v[10:11]
	v_mad_i64_i32 v[164:165], s[18:19], v164, s14, v[10:11]
	v_mad_i64_i32 v[166:167], s[18:19], v166, s14, v[10:11]
	v_mad_i64_i32 v[168:169], s[18:19], v168, s14, v[10:11]
	v_mad_i64_i32 v[170:171], s[18:19], v170, s14, v[10:11]
	global_load_dword v188, v[140:141], off
	global_load_dword v189, v[142:143], off
	global_load_dword v190, v[144:145], off
	global_load_dword v191, v[146:147], off
	global_load_dword v192, v[148:149], off
	global_load_dword v193, v[150:151], off
	global_load_dword v194, v[152:153], off
	global_load_dword v195, v[154:155], off
	global_load_dword v196, v[156:157], off
	global_load_dword v197, v[158:159], off
	global_load_dword v198, v[160:161], off
	global_load_dword v199, v[162:163], off
	global_load_dword v200, v[164:165], off
	global_load_dword v201, v[166:167], off
	global_load_dword v202, v[168:169], off
	global_load_dword v203, v[170:171], off
	s_add_i32 s15, s15, 16
	s_add_i32 s17, s17, 16
	s_add_i32 s16, s16, -16
	v_mad_u64_u32 v[140:141], s[18:19], v173, s13, v[4:5]
	s_cmp_lg_u32 s16, 0
	v_mad_u64_u32 v[142:143], s[18:19], v172, s13, v[4:5]
	v_mad_u64_u32 v[144:145], s[18:19], v175, s13, v[4:5]
	v_mad_u64_u32 v[146:147], s[18:19], v174, s13, v[4:5]
	v_mad_u64_u32 v[148:149], s[18:19], v177, s13, v[4:5]
	v_mad_u64_u32 v[150:151], s[18:19], v176, s13, v[4:5]
	v_mad_u64_u32 v[152:153], s[18:19], v179, s13, v[4:5]
	v_mad_u64_u32 v[154:155], s[18:19], v178, s13, v[4:5]
	v_mad_u64_u32 v[156:157], s[18:19], v181, s13, v[4:5]
	v_mad_u64_u32 v[158:159], s[18:19], v180, s13, v[4:5]
	v_mad_u64_u32 v[160:161], s[18:19], v183, s13, v[4:5]
	v_mad_u64_u32 v[162:163], s[18:19], v182, s13, v[4:5]
	v_mad_u64_u32 v[164:165], s[18:19], v185, s13, v[4:5]
	v_mad_u64_u32 v[166:167], s[18:19], v184, s13, v[4:5]
	v_mad_u64_u32 v[168:169], s[18:19], v187, s13, v[4:5]
	v_mad_u64_u32 v[170:171], s[18:19], v186, s13, v[4:5]
	s_waitcnt vmcnt(31)
	ds_write_b32 v18, v66
	s_waitcnt vmcnt(30)
	ds_write_b32 v20, v67
	s_waitcnt vmcnt(29)
	ds_write_b32 v22, v68
	s_waitcnt vmcnt(28)
	ds_write_b32 v24, v69
	s_waitcnt vmcnt(27)
	ds_write_b32 v26, v70
	s_waitcnt vmcnt(26)
	ds_write_b32 v28, v71
	s_waitcnt vmcnt(25)
	ds_write_b32 v30, v72
	s_waitcnt vmcnt(24)
	ds_write_b32 v32, v73
	s_waitcnt vmcnt(23)
	ds_write_b32 v34, v74
	s_waitcnt vmcnt(22)
	ds_write_b32 v36, v75
	s_waitcnt vmcnt(21)
	ds_write_b32 v38, v76
	s_waitcnt vmcnt(20)
	ds_write_b32 v40, v77
	s_waitcnt vmcnt(19)
	ds_write_b32 v42, v78
	s_waitcnt vmcnt(18)
	ds_write_b32 v44, v79
	s_waitcnt vmcnt(17)
	ds_write_b32 v46, v80
	s_waitcnt vmcnt(16)
	ds_write_b32 v48, v81
	s_waitcnt vmcnt(15)
	ds_write_b32 v140, v188
	s_waitcnt vmcnt(14)
	ds_write_b32 v142, v189
	s_waitcnt vmcnt(13)
	ds_write_b32 v144, v190
	s_waitcnt vmcnt(12)
	ds_write_b32 v146, v191
	s_waitcnt vmcnt(11)
	ds_write_b32 v148, v192
	s_waitcnt vmcnt(10)
	ds_write_b32 v150, v193
	s_waitcnt vmcnt(9)
	ds_write_b32 v152, v194
	s_waitcnt vmcnt(8)
	ds_write_b32 v154, v195
	s_waitcnt vmcnt(7)
	ds_write_b32 v156, v196
	s_waitcnt vmcnt(6)
	ds_write_b32 v158, v197
	s_waitcnt vmcnt(5)
	ds_write_b32 v160, v198
	s_waitcnt vmcnt(4)
	ds_write_b32 v162, v199
	s_waitcnt vmcnt(3)
	ds_write_b32 v164, v200
	s_waitcnt vmcnt(2)
	ds_write_b32 v166, v201
	s_waitcnt vmcnt(1)
	ds_write_b32 v168, v202
	s_waitcnt vmcnt(0)
	ds_write_b32 v170, v203
	s_add_i32 s9, s8, 0xc0
	s_cmpk_gt_i32 s7, 0x69
	s_waitcnt lgkmcnt(0)
	s_cselect_b32 s8, s9, s8
	v_or_b32_e32 v24, s8, v3
	ds_read2_b32 v[10:11], v5 offset1:33
	s_ashr_i32 s7, s6, 31
	v_ashrrev_i32_e32 v25, 31, v24
	s_waitcnt lgkmcnt(0)
	v_cvt_pk_bf16_f32 v18, v10, v11
	ds_read2_b32 v[10:11], v5 offset0:66 offset1:99
	v_lshl_add_u64 v[22:23], s[6:7], 1, v[8:9]
	v_lshlrev_b64 v[24:25], 13, v[24:25]
	s_waitcnt lgkmcnt(0)
	v_cvt_pk_bf16_f32 v19, v10, v11
	ds_read2_b32 v[10:11], v5 offset0:132 offset1:165
	v_lshl_add_u64 v[24:25], v[22:23], 0, v[24:25]
	s_waitcnt lgkmcnt(0)
	v_cvt_pk_bf16_f32 v20, v10, v11
	ds_read2_b32 v[10:11], v5 offset0:198 offset1:231
	s_waitcnt lgkmcnt(0)
	v_cvt_pk_bf16_f32 v21, v10, v11
	global_store_dwordx4 v[24:25], v[18:21], off
	v_or_b32_e32 v24, s8, v13
	ds_read2_b32 v[10:11], v5 offset0:8 offset1:41
	v_ashrrev_i32_e32 v25, 31, v24
	s_waitcnt lgkmcnt(0)
	v_cvt_pk_bf16_f32 v18, v10, v11
	ds_read2_b32 v[10:11], v5 offset0:74 offset1:107
	v_lshlrev_b64 v[24:25], 13, v[24:25]
	s_waitcnt lgkmcnt(0)
	v_cvt_pk_bf16_f32 v19, v10, v11
	ds_read2_b32 v[10:11], v5 offset0:140 offset1:173
	v_lshl_add_u64 v[24:25], v[22:23], 0, v[24:25]
	s_waitcnt lgkmcnt(0)
	v_cvt_pk_bf16_f32 v20, v10, v11
	ds_read2_b32 v[10:11], v5 offset0:206 offset1:239
	s_waitcnt lgkmcnt(0)
	v_cvt_pk_bf16_f32 v21, v10, v11
	global_store_dwordx4 v[24:25], v[18:21], off
	v_or_b32_e32 v24, s8, v16
	ds_read2_b32 v[10:11], v5 offset0:16 offset1:49
	v_ashrrev_i32_e32 v25, 31, v24
	s_waitcnt lgkmcnt(0)
	v_cvt_pk_bf16_f32 v18, v10, v11
	ds_read2_b32 v[10:11], v5 offset0:82 offset1:115
	v_lshlrev_b64 v[24:25], 13, v[24:25]
	s_waitcnt lgkmcnt(0)
	v_cvt_pk_bf16_f32 v19, v10, v11
	ds_read2_b32 v[10:11], v5 offset0:148 offset1:181
	v_lshl_add_u64 v[24:25], v[22:23], 0, v[24:25]
	s_waitcnt lgkmcnt(0)
	v_cvt_pk_bf16_f32 v20, v10, v11
	ds_read2_b32 v[10:11], v5 offset0:214 offset1:247
	s_waitcnt lgkmcnt(0)
	v_cvt_pk_bf16_f32 v21, v10, v11
	global_store_dwordx4 v[24:25], v[18:21], off
	v_or_b32_e32 v24, s8, v17
	ds_read2_b32 v[10:11], v5 offset0:24 offset1:57
	v_ashrrev_i32_e32 v25, 31, v24
	s_waitcnt lgkmcnt(0)
	v_cvt_pk_bf16_f32 v18, v10, v11
	ds_read2_b32 v[10:11], v5 offset0:90 offset1:123
	v_lshlrev_b64 v[24:25], 13, v[24:25]
	s_waitcnt lgkmcnt(0)
	v_cvt_pk_bf16_f32 v19, v10, v11
	ds_read2_b32 v[10:11], v5 offset0:156 offset1:189
	v_lshl_add_u64 v[22:23], v[22:23], 0, v[24:25]
	s_waitcnt lgkmcnt(0)
	v_cvt_pk_bf16_f32 v20, v10, v11
	ds_read2_b32 v[10:11], v5 offset0:222 offset1:255
	s_waitcnt lgkmcnt(0)
	v_cvt_pk_bf16_f32 v21, v10, v11
	global_store_dwordx4 v[22:23], v[18:21], off
	s_waitcnt lgkmcnt(0)
	s_add_i32 s12, s12, s3
	s_cmp_gt_i32 s12, 0xa27f
	s_cbranch_scc0 .LBB0_29

; __device__ __forceinline__ void p0_transpose_item(const float* W, int N, bf16_t* WT, int ldt, int k0, int n0, int nrow0, int kcol0, LAS float* scr, int lane) {
; #pragma unroll 8
;     for (int i = 0; i < 32; ++i) { const int kk = 2 * i + (lane >> 5); scr[kk * 33 + (lane & 31)] = W[(size_t)(k0 + kk) * N + n0 + (lane & 31)]; }
.LBB0_35:
	s_lshl_b32 s18, s17, 1
	s_lshl_b32 s19, s16, 1
	v_or_b32_e32 v50, s18, v1
	v_or_b32_e32 v51, s19, v2
	s_add_i32 s20, s18, 4
	s_add_i32 s21, s19, 4
	s_add_i32 s22, s18, 8
	s_add_i32 s23, s19, 8
	s_add_i32 s24, s18, 12
	s_add_i32 s25, s19, 12
	s_add_i32 s26, s18, 16
	s_add_i32 s27, s19, 16
	s_add_i32 s28, s18, 20
	s_add_i32 s29, s19, 20
	s_add_i32 s30, s18, 24
	s_add_i32 s31, s19, 24
	s_add_i32 s18, s18, 28
	s_add_i32 s19, s19, 28
	v_add_u32_e32 v18, s8, v51
	v_or_b32_e32 v52, s20, v1
	v_or_b32_e32 v53, s21, v2
	v_or_b32_e32 v54, s22, v1
	v_or_b32_e32 v55, s23, v2
	v_or_b32_e32 v56, s24, v1
	v_or_b32_e32 v57, s25, v2
	v_or_b32_e32 v58, s26, v1
	v_or_b32_e32 v59, s27, v2
	v_or_b32_e32 v60, s28, v1
	v_or_b32_e32 v61, s29, v2
	v_or_b32_e32 v62, s30, v1
	v_or_b32_e32 v63, s31, v2
	v_or_b32_e32 v64, s18, v1
	v_or_b32_e32 v65, s19, v2
	v_add_u32_e32 v20, s7, v50
	v_mad_i64_i32 v[18:19], s[18:19], v18, s14, v[10:11]
	v_add_u32_e32 v24, s7, v52
	v_add_u32_e32 v22, s8, v53
	v_add_u32_e32 v28, s7, v54
	v_add_u32_e32 v26, s8, v55
	v_add_u32_e32 v32, s7, v56
	v_add_u32_e32 v30, s8, v57
	v_add_u32_e32 v36, s7, v58
	v_add_u32_e32 v34, s8, v59
	v_add_u32_e32 v40, s7, v60
	v_add_u32_e32 v38, s8, v61
	v_add_u32_e32 v44, s7, v62
	v_add_u32_e32 v42, s8, v63
	v_add_u32_e32 v48, s7, v64
	v_add_u32_e32 v46, s8, v65
	v_mad_i64_i32 v[20:21], s[18:19], v20, s14, v[10:11]
	v_mad_i64_i32 v[22:23], s[18:19], v22, s14, v[10:11]
	v_mad_i64_i32 v[24:25], s[18:19], v24, s14, v[10:11]
	v_mad_i64_i32 v[26:27], s[18:19], v26, s14, v[10:11]
	v_mad_i64_i32 v[28:29], s[18:19], v28, s14, v[10:11]
	v_mad_i64_i32 v[30:31], s[18:19], v30, s14, v[10:11]
	v_mad_i64_i32 v[32:33], s[18:19], v32, s14, v[10:11]
	v_mad_i64_i32 v[34:35], s[18:19], v34, s14, v[10:11]
	v_mad_i64_i32 v[36:37], s[18:19], v36, s14, v[10:11]
	v_mad_i64_i32 v[38:39], s[18:19], v38, s14, v[10:11]
	v_mad_i64_i32 v[40:41], s[18:19], v40, s14, v[10:11]
	v_mad_i64_i32 v[42:43], s[18:19], v42, s14, v[10:11]
	v_mad_i64_i32 v[44:45], s[18:19], v44, s14, v[10:11]
	v_mad_i64_i32 v[46:47], s[18:19], v46, s14, v[10:11]
	v_mad_i64_i32 v[48:49], s[18:19], v48, s14, v[10:11]
	global_load_dword v66, v[18:19], off
	global_load_dword v67, v[20:21], off
	global_load_dword v68, v[22:23], off
	global_load_dword v69, v[24:25], off
	global_load_dword v70, v[26:27], off
	global_load_dword v71, v[28:29], off
	global_load_dword v72, v[30:31], off
	global_load_dword v73, v[32:33], off
	global_load_dword v74, v[34:35], off
	global_load_dword v75, v[36:37], off
	global_load_dword v76, v[38:39], off
	global_load_dword v77, v[40:41], off
	global_load_dword v78, v[42:43], off
	global_load_dword v79, v[44:45], off
	global_load_dword v80, v[46:47], off
	global_load_dword v81, v[48:49], off
	s_add_i32 s16, s16, 16
	s_add_i32 s17, s17, 16
	s_add_i32 s9, s9, -16
	v_mad_u64_u32 v[18:19], s[18:19], v51, s13, v[4:5]
	s_cmp_lg_u32 s9, 0
	v_mad_u64_u32 v[20:21], s[18:19], v50, s13, v[4:5]
	v_mad_u64_u32 v[22:23], s[18:19], v53, s13, v[4:5]
	v_mad_u64_u32 v[24:25], s[18:19], v52, s13, v[4:5]
	v_mad_u64_u32 v[26:27], s[18:19], v55, s13, v[4:5]
	v_mad_u64_u32 v[28:29], s[18:19], v54, s13, v[4:5]
	v_mad_u64_u32 v[30:31], s[18:19], v57, s13, v[4:5]
	v_mad_u64_u32 v[32:33], s[18:19], v56, s13, v[4:5]
	v_mad_u64_u32 v[34:35], s[18:19], v59, s13, v[4:5]
	v_mad_u64_u32 v[36:37], s[18:19], v58, s13, v[4:5]
	v_mad_u64_u32 v[38:39], s[18:19], v61, s13, v[4:5]
	v_mad_u64_u32 v[40:41], s[18:19], v60, s13, v[4:5]
	v_mad_u64_u32 v[42:43], s[18:19], v63, s13, v[4:5]
	v_mad_u64_u32 v[44:45], s[18:19], v62, s13, v[4:5]
	v_mad_u64_u32 v[46:47], s[18:19], v65, s13, v[4:5]
	v_mad_u64_u32 v[48:49], s[18:19], v64, s13, v[4:5]
	s_nop 7
	s_lshl_b32 s18, s17, 1
	s_lshl_b32 s19, s16, 1
	v_or_b32_e32 v172, s18, v1
	v_or_b32_e32 v173, s19, v2
	s_add_i32 s20, s18, 4
	s_add_i32 s21, s19, 4
	s_add_i32 s22, s18, 8
	s_add_i32 s23, s19, 8
	s_add_i32 s24, s18, 12
	s_add_i32 s25, s19, 12
	s_add_i32 s26, s18, 16
	s_add_i32 s27, s19, 16
	s_add_i32 s28, s18, 20
	s_add_i32 s29, s19, 20
	s_add_i32 s30, s18, 24
	s_add_i32 s31, s19, 24
	s_add_i32 s18, s18, 28
	s_add_i32 s19, s19, 28
	v_add_u32_e32 v140, s8, v173
	v_or_b32_e32 v174, s20, v1
	v_or_b32_e32 v175, s21, v2
	v_or_b32_e32 v176, s22, v1
	v_or_b32_e32 v177, s23, v2
	v_or_b32_e32 v178, s24, v1
	v_or_b32_e32 v179, s25, v2
	v_or_b32_e32 v180, s26, v1
	v_or_b32_e32 v181, s27, v2
	v_or_b32_e32 v182, s28, v1
	v_or_b32_e32 v183, s29, v2
	v_or_b32_e32 v184, s30, v1
	v_or_b32_e32 v185, s31, v2
	v_or_b32_e32 v186, s18, v1
	v_or_b32_e32 v187, s19, v2
	v_add_u32_e32 v142, s7, v172
	v_mad_i64_i32 v[140:141], s[18:19], v140, s14, v[10:11]
	v_add_u32_e32 v146, s7, v174
	v_add_u32_e32 v144, s8, v175
	v_add_u32_e32 v150, s7, v176
	v_add_u32_e32 v148, s8, v177
	v_add_u32_e32 v154, s7, v178
	v_add_u32_e32 v152, s8, v179
	v_add_u32_e32 v158, s7, v180
	v_add_u32_e32 v156, s8, v181
	v_add_u32_e32 v162, s7, v182
	v_add_u32_e32 v160, s8, v183
	v_add_u32_e32 v166, s7, v184
	v_add_u32_e32 v164, s8, v185
	v_add_u32_e32 v170, s7, v186
	v_add_u32_e32 v168, s8, v187
	v_mad_i64_i32 v[142:143], s[18:19], v142, s14, v[10:11]
	v_mad_i64_i32 v[144:145], s[18:19], v144, s14, v[10:11]
	v_mad_i64_i32 v[146:147], s[18:19], v146, s14, v[10:11]
	v_mad_i64_i32 v[148:149], s[18:19], v148, s14, v[10:11]
	v_mad_i64_i32 v[150:151], s[18:19], v150, s14, v[10:11]
	v_mad_i64_i32 v[152:153], s[18:19], v152, s14, v[10:11]
	v_mad_i64_i32 v[154:155], s[18:19], v154, s14, v[10:11]
	v_mad_i64_i32 v[156:157], s[18:19], v156, s14, v[10:11]
	v_mad_i64_i32 v[158:159], s[18:19], v158, s14, v[10:11]
	v_mad_i64_i32 v[160:161], s[18:19], v160, s14, v[10:11]
	v_mad_i64_i32 v[162:163], s[18:19], v162, s14, v[10:11]
; #define LAS __attribute__((address_space(3)))
; __device__ __forceinline__ unsigned cvt_pk_bf16(float lo, float hi) { unsigned r; asm volatile("v_cvt_pk_bf16_f32 %0, %1, %2" : "=v"(r) : "v"(lo), "v"(hi)); return r; }
; #define LDS_WAIT() asm volatile("s_waitcnt lgkmcnt(0)" ::: "memory")
; __device__ __forceinline__ void p0_transpose_item(const float* W, int N, bf16_t* WT, int ldt, int k0, int n0, int nrow0, int kcol0, LAS float* scr, int lane) {
; #pragma unroll 8
;     for (int i = 0; i < 32; ++i) { const int kk = 2 * i + (lane >> 5); scr[kk * 33 + (lane & 31)] = W[(size_t)(k0 + kk) * N + n0 + (lane & 31)]; }
;     LDS_WAIT(); asm volatile("" ::: "memory");
;     const int c = lane & 7;
; #pragma unroll
;     for (int j = 0; j < 4; ++j) { const int n = (lane >> 3) + 8 * j; const LAS float* s = scr + (8 * c) * 33 + n;
;         u32x4 o; o.x = cvt_pk_bf16(s[0 * 33], s[1 * 33]); o.y = cvt_pk_bf16(s[2 * 33], s[3 * 33]); o.z = cvt_pk_bf16(s[4 * 33], s[5 * 33]); o.w = cvt_pk_bf16(s[6 * 33], s[7 * 33]);
;         *(u32x4*)(WT + (size_t)(nrow0 + n) * ldt + kcol0 + k0 + 8 * c) = o; }
;     LDS_WAIT(); asm volatile("" ::: "memory");
; }
; __device__ __forceinline__ void p0_prologue(const Frame& F) {
;     ...
;                 for (int it = first; it < nitems; it += NGW) { const int kb = it / nblk, nbk = it % nblk, n0 = nbk * 32;
;                     const int nrow0 = (jb == 0 && n0 >= 3392) ? n0 + 192 : n0;
;                     p0_transpose_item(W, J.N, WT, J.ldt, kb * 64, n0, nrow0, J.kcol0, scr, F.lane); }
	v_mad_i64_i32 v[164:165], s[18:19], v164, s14, v[10:11]
	v_mad_i64_i32 v[166:167], s[18:19], v166, s14, v[10:11]
	v_mad_i64_i32 v[168:169], s[18:19], v168, s14, v[10:11]
	v_mad_i64_i32 v[170:171], s[18:19], v170, s14, v[10:11]
	global_load_dword v188, v[140:141], off
	global_load_dword v189, v[142:143], off
	global_load_dword v190, v[144:145], off
	global_load_dword v191, v[146:147], off
	global_load_dword v192, v[148:149], off
	global_load_dword v193, v[150:151], off
	global_load_dword v194, v[152:153], off
	global_load_dword v195, v[154:155], off
	global_load_dword v196, v[156:157], off
	global_load_dword v197, v[158:159], off
	global_load_dword v198, v[160:161], off
	global_load_dword v199, v[162:163], off
	global_load_dword v200, v[164:165], off
	global_load_dword v201, v[166:167], off
	global_load_dword v202, v[168:169], off
	global_load_dword v203, v[170:171], off
	s_add_i32 s16, s16, 16
	s_add_i32 s17, s17, 16
	s_add_i32 s9, s9, -16
	v_mad_u64_u32 v[140:141], s[18:19], v173, s13, v[4:5]
	s_cmp_lg_u32 s9, 0
	v_mad_u64_u32 v[142:143], s[18:19], v172, s13, v[4:5]
	v_mad_u64_u32 v[144:145], s[18:19], v175, s13, v[4:5]
	v_mad_u64_u32 v[146:147], s[18:19], v174, s13, v[4:5]
	v_mad_u64_u32 v[148:149], s[18:19], v177, s13, v[4:5]
	v_mad_u64_u32 v[150:151], s[18:19], v176, s13, v[4:5]
	v_mad_u64_u32 v[152:153], s[18:19], v179, s13, v[4:5]
	v_mad_u64_u32 v[154:155], s[18:19], v178, s13, v[4:5]
	v_mad_u64_u32 v[156:157], s[18:19], v181, s13, v[4:5]
	v_mad_u64_u32 v[158:159], s[18:19], v180, s13, v[4:5]
	v_mad_u64_u32 v[160:161], s[18:19], v183, s13, v[4:5]
	v_mad_u64_u32 v[162:163], s[18:19], v182, s13, v[4:5]
	v_mad_u64_u32 v[164:165], s[18:19], v185, s13, v[4:5]
	v_mad_u64_u32 v[166:167], s[18:19], v184, s13, v[4:5]
	v_mad_u64_u32 v[168:169], s[18:19], v187, s13, v[4:5]
	v_mad_u64_u32 v[170:171], s[18:19], v186, s13, v[4:5]
	s_waitcnt vmcnt(31)
	ds_write_b32 v18, v66
	s_waitcnt vmcnt(30)
	ds_write_b32 v20, v67
	s_waitcnt vmcnt(29)
	ds_write_b32 v22, v68
	s_waitcnt vmcnt(28)
	ds_write_b32 v24, v69
	s_waitcnt vmcnt(27)
	ds_write_b32 v26, v70
	s_waitcnt vmcnt(26)
	ds_write_b32 v28, v71
	s_waitcnt vmcnt(25)
	ds_write_b32 v30, v72
	s_waitcnt vmcnt(24)
	ds_write_b32 v32, v73
	s_waitcnt vmcnt(23)
	ds_write_b32 v34, v74
	s_waitcnt vmcnt(22)
	ds_write_b32 v36, v75
	s_waitcnt vmcnt(21)
	ds_write_b32 v38, v76
	s_waitcnt vmcnt(20)
	ds_write_b32 v40, v77
	s_waitcnt vmcnt(19)
	ds_write_b32 v42, v78
	s_waitcnt vmcnt(18)
	ds_write_b32 v44, v79
	s_waitcnt vmcnt(17)
	ds_write_b32 v46, v80
	s_waitcnt vmcnt(16)
	ds_write_b32 v48, v81
	s_waitcnt vmcnt(15)
	ds_write_b32 v140, v188
	s_waitcnt vmcnt(14)
	ds_write_b32 v142, v189
	s_waitcnt vmcnt(13)
	ds_write_b32 v144, v190
	s_waitcnt vmcnt(12)
	ds_write_b32 v146, v191
	s_waitcnt vmcnt(11)
	ds_write_b32 v148, v192
	s_waitcnt vmcnt(10)
	ds_write_b32 v150, v193
	s_waitcnt vmcnt(9)
	ds_write_b32 v152, v194
	s_waitcnt vmcnt(8)
	ds_write_b32 v154, v195
	s_waitcnt vmcnt(7)
	ds_write_b32 v156, v196
	s_waitcnt vmcnt(6)
	ds_write_b32 v158, v197
	s_waitcnt vmcnt(5)
	ds_write_b32 v160, v198
	s_waitcnt vmcnt(4)
	ds_write_b32 v162, v199
	s_waitcnt vmcnt(3)
	ds_write_b32 v164, v200
	s_waitcnt vmcnt(2)
	ds_write_b32 v166, v201
	s_waitcnt vmcnt(1)
	ds_write_b32 v168, v202
	s_waitcnt vmcnt(0)
	ds_write_b32 v170, v203
	s_waitcnt lgkmcnt(0)
	ds_read2_b32 v[10:11], v5 offset1:33
	v_or_b32_e32 v24, s6, v3
	s_waitcnt lgkmcnt(0)
	v_cvt_pk_bf16_f32 v18, v10, v11
	ds_read2_b32 v[10:11], v5 offset0:66 offset1:99
	s_ashr_i32 s9, s8, 31
	v_mul_lo_u32 v24, v24, s15
	s_waitcnt lgkmcnt(0)
	v_cvt_pk_bf16_f32 v19, v10, v11
	ds_read2_b32 v[10:11], v5 offset0:132 offset1:165
	v_lshl_add_u64 v[22:23], s[8:9], 1, v[8:9]
	v_ashrrev_i32_e32 v25, 31, v24
	s_waitcnt lgkmcnt(0)
	v_cvt_pk_bf16_f32 v20, v10, v11
	ds_read2_b32 v[10:11], v5 offset0:198 offset1:231
	v_lshl_add_u64 v[24:25], v[22:23], 0, v[24:25]
	s_waitcnt lgkmcnt(0)
	v_cvt_pk_bf16_f32 v21, v10, v11
	ds_read2_b32 v[10:11], v5 offset0:8 offset1:41
	global_store_dwordx4 v[24:25], v[18:21], off
	v_or_b32_e32 v24, s6, v13
	v_mul_lo_u32 v24, v24, s15
	s_waitcnt lgkmcnt(0)
	v_cvt_pk_bf16_f32 v18, v10, v11
	ds_read2_b32 v[10:11], v5 offset0:74 offset1:107
	s_waitcnt lgkmcnt(0)
	v_cvt_pk_bf16_f32 v19, v10, v11
	ds_read2_b32 v[10:11], v5 offset0:140 offset1:173
	v_ashrrev_i32_e32 v25, 31, v24
	s_waitcnt lgkmcnt(0)
	v_cvt_pk_bf16_f32 v20, v10, v11
	ds_read2_b32 v[10:11], v5 offset0:206 offset1:239
	v_lshl_add_u64 v[24:25], v[22:23], 0, v[24:25]
	s_waitcnt lgkmcnt(0)
	v_cvt_pk_bf16_f32 v21, v10, v11
	ds_read2_b32 v[10:11], v5 offset0:16 offset1:49
	global_store_dwordx4 v[24:25], v[18:21], off
	v_or_b32_e32 v24, s6, v16
	v_mul_lo_u32 v24, v24, s15
	s_waitcnt lgkmcnt(0)
	v_cvt_pk_bf16_f32 v18, v10, v11
	ds_read2_b32 v[10:11], v5 offset0:82 offset1:115
	s_waitcnt lgkmcnt(0)
	v_cvt_pk_bf16_f32 v19, v10, v11
	ds_read2_b32 v[10:11], v5 offset0:148 offset1:181
	v_ashrrev_i32_e32 v25, 31, v24
	s_waitcnt lgkmcnt(0)
	v_cvt_pk_bf16_f32 v20, v10, v11
	ds_read2_b32 v[10:11], v5 offset0:214 offset1:247
	s_waitcnt lgkmcnt(0)
	v_cvt_pk_bf16_f32 v21, v10, v11
	v_lshl_add_u64 v[24:25], v[22:23], 0, v[24:25]
	global_store_dwordx4 v[24:25], v[18:21], off
	ds_read2_b32 v[10:11], v5 offset0:24 offset1:57
	s_add_i32 s12, s12, s3
	v_or_b32_e32 v21, s6, v17
	v_mul_lo_u32 v24, v21, s15
	s_waitcnt lgkmcnt(0)
	v_cvt_pk_bf16_f32 v18, v10, v11
	ds_read2_b32 v[10:11], v5 offset0:90 offset1:123
	v_ashrrev_i32_e32 v25, 31, v24
	s_waitcnt lgkmcnt(0)
	v_cvt_pk_bf16_f32 v19, v10, v11
	ds_read2_b32 v[10:11], v5 offset0:156 offset1:189
	v_lshl_add_u64 v[22:23], v[22:23], 0, v[24:25]
	s_waitcnt lgkmcnt(0)
	v_cvt_pk_bf16_f32 v20, v10, v11
	ds_read2_b32 v[10:11], v5 offset0:222 offset1:255
	s_waitcnt lgkmcnt(0)
	v_cvt_pk_bf16_f32 v21, v10, v11
	global_store_dwordx4 v[22:23], v[18:21], off
	s_waitcnt lgkmcnt(0)
	s_cmpk_lt_i32 s12, 0x480
	s_cbranch_scc1 .LBB0_34

; __device__ __forceinline__ void p0_transpose_item(const float* W, int N, bf16_t* WT, int ldt, int k0, int n0, int nrow0, int kcol0, LAS float* scr, int lane) {
; #pragma unroll 8
;     for (int i = 0; i < 32; ++i) { const int kk = 2 * i + (lane >> 5); scr[kk * 33 + (lane & 31)] = W[(size_t)(k0 + kk) * N + n0 + (lane & 31)]; }
.LBB0_75:
	s_lshl_b32 s18, s17, 1
	s_lshl_b32 s19, s16, 1
	v_or_b32_e32 v50, s18, v1
	v_or_b32_e32 v51, s19, v2
	s_add_i32 s20, s18, 4
	s_add_i32 s21, s19, 4
	s_add_i32 s22, s18, 8
	s_add_i32 s23, s19, 8
	s_add_i32 s24, s18, 12
	s_add_i32 s25, s19, 12
	s_add_i32 s26, s18, 16
	s_add_i32 s27, s19, 16
	s_add_i32 s28, s18, 20
	s_add_i32 s29, s19, 20
	s_add_i32 s30, s18, 24
	s_add_i32 s31, s19, 24
	s_add_i32 s18, s18, 28
	s_add_i32 s19, s19, 28
	v_add_u32_e32 v18, s6, v51
	v_or_b32_e32 v52, s20, v1
	v_or_b32_e32 v53, s21, v2
	v_or_b32_e32 v54, s22, v1
	v_or_b32_e32 v55, s23, v2
	v_or_b32_e32 v56, s24, v1
	v_or_b32_e32 v57, s25, v2
	v_or_b32_e32 v58, s26, v1
	v_or_b32_e32 v59, s27, v2
	v_or_b32_e32 v60, s28, v1
	v_or_b32_e32 v61, s29, v2
	v_or_b32_e32 v62, s30, v1
	v_or_b32_e32 v63, s31, v2
	v_or_b32_e32 v64, s18, v1
	v_or_b32_e32 v65, s19, v2
	v_add_u32_e32 v20, s9, v50
	v_mad_i64_i32 v[18:19], s[18:19], v18, s14, v[10:11]
	v_add_u32_e32 v24, s9, v52
	v_add_u32_e32 v22, s6, v53
	v_add_u32_e32 v28, s9, v54
	v_add_u32_e32 v26, s6, v55
	v_add_u32_e32 v32, s9, v56
	v_add_u32_e32 v30, s6, v57
	v_add_u32_e32 v36, s9, v58
	v_add_u32_e32 v34, s6, v59
	v_add_u32_e32 v40, s9, v60
	v_add_u32_e32 v38, s6, v61
	v_add_u32_e32 v44, s9, v62
	v_add_u32_e32 v42, s6, v63
	v_add_u32_e32 v48, s9, v64
	v_add_u32_e32 v46, s6, v65
	v_mad_i64_i32 v[20:21], s[18:19], v20, s14, v[10:11]
	v_mad_i64_i32 v[22:23], s[18:19], v22, s14, v[10:11]
	v_mad_i64_i32 v[24:25], s[18:19], v24, s14, v[10:11]
	v_mad_i64_i32 v[26:27], s[18:19], v26, s14, v[10:11]
	v_mad_i64_i32 v[28:29], s[18:19], v28, s14, v[10:11]
	v_mad_i64_i32 v[30:31], s[18:19], v30, s14, v[10:11]
	v_mad_i64_i32 v[32:33], s[18:19], v32, s14, v[10:11]
	v_mad_i64_i32 v[34:35], s[18:19], v34, s14, v[10:11]
	v_mad_i64_i32 v[36:37], s[18:19], v36, s14, v[10:11]
	v_mad_i64_i32 v[38:39], s[18:19], v38, s14, v[10:11]
	v_mad_i64_i32 v[40:41], s[18:19], v40, s14, v[10:11]
	v_mad_i64_i32 v[42:43], s[18:19], v42, s14, v[10:11]
	v_mad_i64_i32 v[44:45], s[18:19], v44, s14, v[10:11]
	v_mad_i64_i32 v[46:47], s[18:19], v46, s14, v[10:11]
	v_mad_i64_i32 v[48:49], s[18:19], v48, s14, v[10:11]
	global_load_dword v66, v[18:19], off
	global_load_dword v67, v[20:21], off
	global_load_dword v68, v[22:23], off
	global_load_dword v69, v[24:25], off
	global_load_dword v70, v[26:27], off
	global_load_dword v71, v[28:29], off
	global_load_dword v72, v[30:31], off
	global_load_dword v73, v[32:33], off
	global_load_dword v74, v[34:35], off
	global_load_dword v75, v[36:37], off
	global_load_dword v76, v[38:39], off
	global_load_dword v77, v[40:41], off
	global_load_dword v78, v[42:43], off
	global_load_dword v79, v[44:45], off
	global_load_dword v80, v[46:47], off
	global_load_dword v81, v[48:49], off
	s_add_i32 s16, s16, 16
	s_add_i32 s17, s17, 16
	s_add_i32 s15, s15, -16
	v_mad_u64_u32 v[18:19], s[18:19], v51, s13, v[6:7]
	s_cmp_lg_u32 s15, 0
	v_mad_u64_u32 v[20:21], s[18:19], v50, s13, v[6:7]
	v_mad_u64_u32 v[22:23], s[18:19], v53, s13, v[6:7]
	v_mad_u64_u32 v[24:25], s[18:19], v52, s13, v[6:7]
	v_mad_u64_u32 v[26:27], s[18:19], v55, s13, v[6:7]
	v_mad_u64_u32 v[28:29], s[18:19], v54, s13, v[6:7]
	v_mad_u64_u32 v[30:31], s[18:19], v57, s13, v[6:7]
	v_mad_u64_u32 v[32:33], s[18:19], v56, s13, v[6:7]
	v_mad_u64_u32 v[34:35], s[18:19], v59, s13, v[6:7]
	v_mad_u64_u32 v[36:37], s[18:19], v58, s13, v[6:7]
	v_mad_u64_u32 v[38:39], s[18:19], v61, s13, v[6:7]
	v_mad_u64_u32 v[40:41], s[18:19], v60, s13, v[6:7]
	v_mad_u64_u32 v[42:43], s[18:19], v63, s13, v[6:7]
	v_mad_u64_u32 v[44:45], s[18:19], v62, s13, v[6:7]
	v_mad_u64_u32 v[46:47], s[18:19], v65, s13, v[6:7]
	v_mad_u64_u32 v[48:49], s[18:19], v64, s13, v[6:7]
	s_nop 7
	s_lshl_b32 s18, s17, 1
	s_lshl_b32 s19, s16, 1
	v_or_b32_e32 v172, s18, v1
	v_or_b32_e32 v173, s19, v2
	s_add_i32 s20, s18, 4
	s_add_i32 s21, s19, 4
	s_add_i32 s22, s18, 8
	s_add_i32 s23, s19, 8
	s_add_i32 s24, s18, 12
	s_add_i32 s25, s19, 12
	s_add_i32 s26, s18, 16
	s_add_i32 s27, s19, 16
	s_add_i32 s28, s18, 20
	s_add_i32 s29, s19, 20
	s_add_i32 s30, s18, 24
	s_add_i32 s31, s19, 24
	s_add_i32 s18, s18, 28
	s_add_i32 s19, s19, 28
	v_add_u32_e32 v140, s6, v173
	v_or_b32_e32 v174, s20, v1
	v_or_b32_e32 v175, s21, v2
	v_or_b32_e32 v176, s22, v1
	v_or_b32_e32 v177, s23, v2
	v_or_b32_e32 v178, s24, v1
	v_or_b32_e32 v179, s25, v2
	v_or_b32_e32 v180, s26, v1
	v_or_b32_e32 v181, s27, v2
	v_or_b32_e32 v182, s28, v1
	v_or_b32_e32 v183, s29, v2
	v_or_b32_e32 v184, s30, v1
	v_or_b32_e32 v185, s31, v2
	v_or_b32_e32 v186, s18, v1
	v_or_b32_e32 v187, s19, v2
	v_add_u32_e32 v142, s9, v172
	v_mad_i64_i32 v[140:141], s[18:19], v140, s14, v[10:11]
	v_add_u32_e32 v146, s9, v174
	v_add_u32_e32 v144, s6, v175
	v_add_u32_e32 v150, s9, v176
	v_add_u32_e32 v148, s6, v177
	v_add_u32_e32 v154, s9, v178
	v_add_u32_e32 v152, s6, v179
	v_add_u32_e32 v158, s9, v180
	v_add_u32_e32 v156, s6, v181
	v_add_u32_e32 v162, s9, v182
	v_add_u32_e32 v160, s6, v183
	v_add_u32_e32 v166, s9, v184
	v_add_u32_e32 v164, s6, v185
	v_add_u32_e32 v170, s9, v186
	v_add_u32_e32 v168, s6, v187
	v_mad_i64_i32 v[142:143], s[18:19], v142, s14, v[10:11]
	v_mad_i64_i32 v[144:145], s[18:19], v144, s14, v[10:11]
	v_mad_i64_i32 v[146:147], s[18:19], v146, s14, v[10:11]
	v_mad_i64_i32 v[148:149], s[18:19], v148, s14, v[10:11]
	v_mad_i64_i32 v[150:151], s[18:19], v150, s14, v[10:11]
	v_mad_i64_i32 v[152:153], s[18:19], v152, s14, v[10:11]
	v_mad_i64_i32 v[154:155], s[18:19], v154, s14, v[10:11]
	v_mad_i64_i32 v[156:157], s[18:19], v156, s14, v[10:11]
	v_mad_i64_i32 v[158:159], s[18:19], v158, s14, v[10:11]
	v_mad_i64_i32 v[160:161], s[18:19], v160, s14, v[10:11]
; #define LAS __attribute__((address_space(3)))
; __device__ __forceinline__ unsigned cvt_pk_bf16(float lo, float hi) { unsigned r; asm volatile("v_cvt_pk_bf16_f32 %0, %1, %2" : "=v"(r) : "v"(lo), "v"(hi)); return r; }
; #define LDS_WAIT() asm volatile("s_waitcnt lgkmcnt(0)" ::: "memory")
; __device__ __forceinline__ void p0_transpose_item(const float* W, int N, bf16_t* WT, int ldt, int k0, int n0, int nrow0, int kcol0, LAS float* scr, int lane) {
; #pragma unroll 8
;     for (int i = 0; i < 32; ++i) { const int kk = 2 * i + (lane >> 5); scr[kk * 33 + (lane & 31)] = W[(size_t)(k0 + kk) * N + n0 + (lane & 31)]; }
;     LDS_WAIT(); asm volatile("" ::: "memory");
;     const int c = lane & 7;
; #pragma unroll
;     for (int j = 0; j < 4; ++j) { const int n = (lane >> 3) + 8 * j; const LAS float* s = scr + (8 * c) * 33 + n;
;         u32x4 o; o.x = cvt_pk_bf16(s[0 * 33], s[1 * 33]); o.y = cvt_pk_bf16(s[2 * 33], s[3 * 33]); o.z = cvt_pk_bf16(s[4 * 33], s[5 * 33]); o.w = cvt_pk_bf16(s[6 * 33], s[7 * 33]);
;         *(u32x4*)(WT + (size_t)(nrow0 + n) * ldt + kcol0 + k0 + 8 * c) = o; }
;     LDS_WAIT(); asm volatile("" ::: "memory");
; }
; __device__ __forceinline__ void p0_prologue(const Frame& F) {
;     ...
;                 for (int it = first; it < nitems; it += NGW) { const int kb = it / nblk, nbk = it % nblk, n0 = nbk * 32;
;                     const int nrow0 = (jb == 0 && n0 >= 3392) ? n0 + 192 : n0;
;                     p0_transpose_item(W, J.N, WT, J.ldt, kb * 64, n0, nrow0, J.kcol0, scr, F.lane); }
	v_mad_i64_i32 v[162:163], s[18:19], v162, s14, v[10:11]
	v_mad_i64_i32 v[164:165], s[18:19], v164, s14, v[10:11]
	v_mad_i64_i32 v[166:167], s[18:19], v166, s14, v[10:11]
	v_mad_i64_i32 v[168:169], s[18:19], v168, s14, v[10:11]
	v_mad_i64_i32 v[170:171], s[18:19], v170, s14, v[10:11]
	global_load_dword v188, v[140:141], off
	global_load_dword v189, v[142:143], off
	global_load_dword v190, v[144:145], off
	global_load_dword v191, v[146:147], off
	global_load_dword v192, v[148:149], off
	global_load_dword v193, v[150:151], off
	global_load_dword v194, v[152:153], off
	global_load_dword v195, v[154:155], off
	global_load_dword v196, v[156:157], off
	global_load_dword v197, v[158:159], off
	global_load_dword v198, v[160:161], off
	global_load_dword v199, v[162:163], off
	global_load_dword v200, v[164:165], off
	global_load_dword v201, v[166:167], off
	global_load_dword v202, v[168:169], off
	global_load_dword v203, v[170:171], off
	s_add_i32 s16, s16, 16
	s_add_i32 s17, s17, 16
	s_add_i32 s15, s15, -16
	v_mad_u64_u32 v[140:141], s[18:19], v173, s13, v[6:7]
	s_cmp_lg_u32 s15, 0
	v_mad_u64_u32 v[142:143], s[18:19], v172, s13, v[6:7]
	v_mad_u64_u32 v[144:145], s[18:19], v175, s13, v[6:7]
	v_mad_u64_u32 v[146:147], s[18:19], v174, s13, v[6:7]
	v_mad_u64_u32 v[148:149], s[18:19], v177, s13, v[6:7]
	v_mad_u64_u32 v[150:151], s[18:19], v176, s13, v[6:7]
	v_mad_u64_u32 v[152:153], s[18:19], v179, s13, v[6:7]
	v_mad_u64_u32 v[154:155], s[18:19], v178, s13, v[6:7]
	v_mad_u64_u32 v[156:157], s[18:19], v181, s13, v[6:7]
	v_mad_u64_u32 v[158:159], s[18:19], v180, s13, v[6:7]
	v_mad_u64_u32 v[160:161], s[18:19], v183, s13, v[6:7]
	v_mad_u64_u32 v[162:163], s[18:19], v182, s13, v[6:7]
	v_mad_u64_u32 v[164:165], s[18:19], v185, s13, v[6:7]
	v_mad_u64_u32 v[166:167], s[18:19], v184, s13, v[6:7]
	v_mad_u64_u32 v[168:169], s[18:19], v187, s13, v[6:7]
	v_mad_u64_u32 v[170:171], s[18:19], v186, s13, v[6:7]
	s_waitcnt vmcnt(31)
	ds_write_b32 v18, v66
	s_waitcnt vmcnt(30)
	ds_write_b32 v20, v67
	s_waitcnt vmcnt(29)
	ds_write_b32 v22, v68
	s_waitcnt vmcnt(28)
	ds_write_b32 v24, v69
	s_waitcnt vmcnt(27)
	ds_write_b32 v26, v70
	s_waitcnt vmcnt(26)
	ds_write_b32 v28, v71
	s_waitcnt vmcnt(25)
	ds_write_b32 v30, v72
	s_waitcnt vmcnt(24)
	ds_write_b32 v32, v73
	s_waitcnt vmcnt(23)
	ds_write_b32 v34, v74
	s_waitcnt vmcnt(22)
	ds_write_b32 v36, v75
	s_waitcnt vmcnt(21)
	ds_write_b32 v38, v76
	s_waitcnt vmcnt(20)
	ds_write_b32 v40, v77
	s_waitcnt vmcnt(19)
	ds_write_b32 v42, v78
	s_waitcnt vmcnt(18)
	ds_write_b32 v44, v79
	s_waitcnt vmcnt(17)
	ds_write_b32 v46, v80
	s_waitcnt vmcnt(16)
	ds_write_b32 v48, v81
	s_waitcnt vmcnt(15)
	ds_write_b32 v140, v188
	s_waitcnt vmcnt(14)
	ds_write_b32 v142, v189
	s_waitcnt vmcnt(13)
	ds_write_b32 v144, v190
	s_waitcnt vmcnt(12)
	ds_write_b32 v146, v191
	s_waitcnt vmcnt(11)
	ds_write_b32 v148, v192
	s_waitcnt vmcnt(10)
	ds_write_b32 v150, v193
	s_waitcnt vmcnt(9)
	ds_write_b32 v152, v194
	s_waitcnt vmcnt(8)
	ds_write_b32 v154, v195
	s_waitcnt vmcnt(7)
	ds_write_b32 v156, v196
	s_waitcnt vmcnt(6)
	ds_write_b32 v158, v197
	s_waitcnt vmcnt(5)
	ds_write_b32 v160, v198
	s_waitcnt vmcnt(4)
	ds_write_b32 v162, v199
	s_waitcnt vmcnt(3)
	ds_write_b32 v164, v200
	s_waitcnt vmcnt(2)
	ds_write_b32 v166, v201
	s_waitcnt vmcnt(1)
	ds_write_b32 v168, v202
	s_waitcnt vmcnt(0)
	ds_write_b32 v170, v203
	s_add_i32 s9, s8, 0xc0
	s_cmpk_gt_i32 s7, 0x69
	s_waitcnt lgkmcnt(0)
	s_cselect_b32 s8, s9, s8
	v_or_b32_e32 v24, s8, v3
	ds_read2_b32 v[10:11], v7 offset1:33
	s_ashr_i32 s7, s6, 31
	v_ashrrev_i32_e32 v25, 31, v24
	s_waitcnt lgkmcnt(0)
	v_cvt_pk_bf16_f32 v18, v10, v11
	ds_read2_b32 v[10:11], v7 offset0:66 offset1:99
	v_lshl_add_u64 v[22:23], s[6:7], 1, v[8:9]
	v_lshlrev_b64 v[24:25], 13, v[24:25]
	s_waitcnt lgkmcnt(0)
	v_cvt_pk_bf16_f32 v19, v10, v11
	ds_read2_b32 v[10:11], v7 offset0:132 offset1:165
	v_lshl_add_u64 v[24:25], v[22:23], 0, v[24:25]
	s_waitcnt lgkmcnt(0)
	v_cvt_pk_bf16_f32 v20, v10, v11
	ds_read2_b32 v[10:11], v7 offset0:198 offset1:231
	s_waitcnt lgkmcnt(0)
	v_cvt_pk_bf16_f32 v21, v10, v11
	global_store_dwordx4 v[24:25], v[18:21], off
	v_or_b32_e32 v24, s8, v13
	ds_read2_b32 v[10:11], v7 offset0:8 offset1:41
	v_ashrrev_i32_e32 v25, 31, v24
	s_waitcnt lgkmcnt(0)
	v_cvt_pk_bf16_f32 v18, v10, v11
	ds_read2_b32 v[10:11], v7 offset0:74 offset1:107
	v_lshlrev_b64 v[24:25], 13, v[24:25]
	s_waitcnt lgkmcnt(0)
	v_cvt_pk_bf16_f32 v19, v10, v11
	ds_read2_b32 v[10:11], v7 offset0:140 offset1:173
	v_lshl_add_u64 v[24:25], v[22:23], 0, v[24:25]
	s_waitcnt lgkmcnt(0)
	v_cvt_pk_bf16_f32 v20, v10, v11
	ds_read2_b32 v[10:11], v7 offset0:206 offset1:239
	s_waitcnt lgkmcnt(0)
	v_cvt_pk_bf16_f32 v21, v10, v11
	global_store_dwordx4 v[24:25], v[18:21], off
	v_or_b32_e32 v24, s8, v16
	ds_read2_b32 v[10:11], v7 offset0:16 offset1:49
	v_ashrrev_i32_e32 v25, 31, v24
	s_waitcnt lgkmcnt(0)
	v_cvt_pk_bf16_f32 v18, v10, v11
	ds_read2_b32 v[10:11], v7 offset0:82 offset1:115
	v_lshlrev_b64 v[24:25], 13, v[24:25]
	s_waitcnt lgkmcnt(0)
	v_cvt_pk_bf16_f32 v19, v10, v11
	ds_read2_b32 v[10:11], v7 offset0:148 offset1:181
	v_lshl_add_u64 v[24:25], v[22:23], 0, v[24:25]
	s_waitcnt lgkmcnt(0)
	v_cvt_pk_bf16_f32 v20, v10, v11
	ds_read2_b32 v[10:11], v7 offset0:214 offset1:247
	s_waitcnt lgkmcnt(0)
	v_cvt_pk_bf16_f32 v21, v10, v11
	global_store_dwordx4 v[24:25], v[18:21], off
	v_or_b32_e32 v24, s8, v17
	ds_read2_b32 v[10:11], v7 offset0:24 offset1:57
	v_ashrrev_i32_e32 v25, 31, v24
	s_waitcnt lgkmcnt(0)
	v_cvt_pk_bf16_f32 v18, v10, v11
	ds_read2_b32 v[10:11], v7 offset0:90 offset1:123
	v_lshlrev_b64 v[24:25], 13, v[24:25]
	s_waitcnt lgkmcnt(0)
	v_cvt_pk_bf16_f32 v19, v10, v11
	ds_read2_b32 v[10:11], v7 offset0:156 offset1:189
	v_lshl_add_u64 v[22:23], v[22:23], 0, v[24:25]
	s_waitcnt lgkmcnt(0)
	v_cvt_pk_bf16_f32 v20, v10, v11
	ds_read2_b32 v[10:11], v7 offset0:222 offset1:255
	s_waitcnt lgkmcnt(0)
	v_cvt_pk_bf16_f32 v21, v10, v11
	global_store_dwordx4 v[22:23], v[18:21], off
	s_waitcnt lgkmcnt(0)
	s_add_i32 s12, s12, s3
	s_cmp_lt_i32 s12, 0xa280
	s_cbranch_scc1 .LBB0_74

; __device__ __forceinline__ void p0_transpose_item(const float* W, int N, bf16_t* WT, int ldt, int k0, int n0, int nrow0, int kcol0, LAS float* scr, int lane) {
; #pragma unroll 8
;     for (int i = 0; i < 32; ++i) { const int kk = 2 * i + (lane >> 5); scr[kk * 33 + (lane & 31)] = W[(size_t)(k0 + kk) * N + n0 + (lane & 31)]; }
.LBB0_80:
	s_lshl_b32 s18, s17, 1
	s_lshl_b32 s19, s16, 1
	v_or_b32_e32 v50, s18, v1
	v_or_b32_e32 v51, s19, v2
	s_add_i32 s20, s18, 4
	s_add_i32 s21, s19, 4
	s_add_i32 s22, s18, 8
	s_add_i32 s23, s19, 8
	s_add_i32 s24, s18, 12
	s_add_i32 s25, s19, 12
	s_add_i32 s26, s18, 16
	s_add_i32 s27, s19, 16
	s_add_i32 s28, s18, 20
	s_add_i32 s29, s19, 20
	s_add_i32 s30, s18, 24
	s_add_i32 s31, s19, 24
	s_add_i32 s18, s18, 28
	s_add_i32 s19, s19, 28
	v_add_u32_e32 v18, s8, v51
	v_or_b32_e32 v52, s20, v1
	v_or_b32_e32 v53, s21, v2
	v_or_b32_e32 v54, s22, v1
	v_or_b32_e32 v55, s23, v2
	v_or_b32_e32 v56, s24, v1
	v_or_b32_e32 v57, s25, v2
	v_or_b32_e32 v58, s26, v1
	v_or_b32_e32 v59, s27, v2
	v_or_b32_e32 v60, s28, v1
	v_or_b32_e32 v61, s29, v2
	v_or_b32_e32 v62, s30, v1
	v_or_b32_e32 v63, s31, v2
	v_or_b32_e32 v64, s18, v1
	v_or_b32_e32 v65, s19, v2
	v_add_u32_e32 v20, s7, v50
	v_mad_i64_i32 v[18:19], s[18:19], v18, s14, v[10:11]
	v_add_u32_e32 v24, s7, v52
	v_add_u32_e32 v22, s8, v53
	v_add_u32_e32 v28, s7, v54
	v_add_u32_e32 v26, s8, v55
	v_add_u32_e32 v32, s7, v56
	v_add_u32_e32 v30, s8, v57
	v_add_u32_e32 v36, s7, v58
	v_add_u32_e32 v34, s8, v59
	v_add_u32_e32 v40, s7, v60
	v_add_u32_e32 v38, s8, v61
	v_add_u32_e32 v44, s7, v62
	v_add_u32_e32 v42, s8, v63
	v_add_u32_e32 v48, s7, v64
	v_add_u32_e32 v46, s8, v65
	v_mad_i64_i32 v[20:21], s[18:19], v20, s14, v[10:11]
	v_mad_i64_i32 v[22:23], s[18:19], v22, s14, v[10:11]
	v_mad_i64_i32 v[24:25], s[18:19], v24, s14, v[10:11]
	v_mad_i64_i32 v[26:27], s[18:19], v26, s14, v[10:11]
	v_mad_i64_i32 v[28:29], s[18:19], v28, s14, v[10:11]
	v_mad_i64_i32 v[30:31], s[18:19], v30, s14, v[10:11]
	v_mad_i64_i32 v[32:33], s[18:19], v32, s14, v[10:11]
	v_mad_i64_i32 v[34:35], s[18:19], v34, s14, v[10:11]
	v_mad_i64_i32 v[36:37], s[18:19], v36, s14, v[10:11]
	v_mad_i64_i32 v[38:39], s[18:19], v38, s14, v[10:11]
	v_mad_i64_i32 v[40:41], s[18:19], v40, s14, v[10:11]
	v_mad_i64_i32 v[42:43], s[18:19], v42, s14, v[10:11]
	v_mad_i64_i32 v[44:45], s[18:19], v44, s14, v[10:11]
	v_mad_i64_i32 v[46:47], s[18:19], v46, s14, v[10:11]
	v_mad_i64_i32 v[48:49], s[18:19], v48, s14, v[10:11]
	global_load_dword v66, v[18:19], off
	global_load_dword v67, v[20:21], off
	global_load_dword v68, v[22:23], off
	global_load_dword v69, v[24:25], off
	global_load_dword v70, v[26:27], off
	global_load_dword v71, v[28:29], off
	global_load_dword v72, v[30:31], off
	global_load_dword v73, v[32:33], off
	global_load_dword v74, v[34:35], off
	global_load_dword v75, v[36:37], off
	global_load_dword v76, v[38:39], off
	global_load_dword v77, v[40:41], off
	global_load_dword v78, v[42:43], off
	global_load_dword v79, v[44:45], off
	global_load_dword v80, v[46:47], off
	global_load_dword v81, v[48:49], off
	s_add_i32 s16, s16, 16
	s_add_i32 s17, s17, 16
	s_add_i32 s9, s9, -16
	v_mad_u64_u32 v[18:19], s[18:19], v51, s13, v[6:7]
	s_cmp_lg_u32 s9, 0
	v_mad_u64_u32 v[20:21], s[18:19], v50, s13, v[6:7]
	v_mad_u64_u32 v[22:23], s[18:19], v53, s13, v[6:7]
	v_mad_u64_u32 v[24:25], s[18:19], v52, s13, v[6:7]
	v_mad_u64_u32 v[26:27], s[18:19], v55, s13, v[6:7]
	v_mad_u64_u32 v[28:29], s[18:19], v54, s13, v[6:7]
	v_mad_u64_u32 v[30:31], s[18:19], v57, s13, v[6:7]
	v_mad_u64_u32 v[32:33], s[18:19], v56, s13, v[6:7]
	v_mad_u64_u32 v[34:35], s[18:19], v59, s13, v[6:7]
	v_mad_u64_u32 v[36:37], s[18:19], v58, s13, v[6:7]
	v_mad_u64_u32 v[38:39], s[18:19], v61, s13, v[6:7]
	v_mad_u64_u32 v[40:41], s[18:19], v60, s13, v[6:7]
	v_mad_u64_u32 v[42:43], s[18:19], v63, s13, v[6:7]
	v_mad_u64_u32 v[44:45], s[18:19], v62, s13, v[6:7]
	v_mad_u64_u32 v[46:47], s[18:19], v65, s13, v[6:7]
	v_mad_u64_u32 v[48:49], s[18:19], v64, s13, v[6:7]
	s_nop 7
	s_lshl_b32 s18, s17, 1
	s_lshl_b32 s19, s16, 1
	v_or_b32_e32 v172, s18, v1
	v_or_b32_e32 v173, s19, v2
	s_add_i32 s20, s18, 4
	s_add_i32 s21, s19, 4
	s_add_i32 s22, s18, 8
	s_add_i32 s23, s19, 8
	s_add_i32 s24, s18, 12
	s_add_i32 s25, s19, 12
	s_add_i32 s26, s18, 16
	s_add_i32 s27, s19, 16
	s_add_i32 s28, s18, 20
	s_add_i32 s29, s19, 20
	s_add_i32 s30, s18, 24
	s_add_i32 s31, s19, 24
	s_add_i32 s18, s18, 28
	s_add_i32 s19, s19, 28
	v_add_u32_e32 v140, s8, v173
	v_or_b32_e32 v174, s20, v1
	v_or_b32_e32 v175, s21, v2
	v_or_b32_e32 v176, s22, v1
	v_or_b32_e32 v177, s23, v2
	v_or_b32_e32 v178, s24, v1
	v_or_b32_e32 v179, s25, v2
	v_or_b32_e32 v180, s26, v1
	v_or_b32_e32 v181, s27, v2
	v_or_b32_e32 v182, s28, v1
	v_or_b32_e32 v183, s29, v2
	v_or_b32_e32 v184, s30, v1
	v_or_b32_e32 v185, s31, v2
	v_or_b32_e32 v186, s18, v1
	v_or_b32_e32 v187, s19, v2
	v_add_u32_e32 v142, s7, v172
	v_mad_i64_i32 v[140:141], s[18:19], v140, s14, v[10:11]
	v_add_u32_e32 v146, s7, v174
	v_add_u32_e32 v144, s8, v175
	v_add_u32_e32 v150, s7, v176
	v_add_u32_e32 v148, s8, v177
	v_add_u32_e32 v154, s7, v178
	v_add_u32_e32 v152, s8, v179
	v_add_u32_e32 v158, s7, v180
	v_add_u32_e32 v156, s8, v181
	v_add_u32_e32 v162, s7, v182
	v_add_u32_e32 v160, s8, v183
	v_add_u32_e32 v166, s7, v184
	v_add_u32_e32 v164, s8, v185
	v_add_u32_e32 v170, s7, v186
	v_add_u32_e32 v168, s8, v187
	v_mad_i64_i32 v[142:143], s[18:19], v142, s14, v[10:11]
	v_mad_i64_i32 v[144:145], s[18:19], v144, s14, v[10:11]
	v_mad_i64_i32 v[146:147], s[18:19], v146, s14, v[10:11]
	v_mad_i64_i32 v[148:149], s[18:19], v148, s14, v[10:11]
	v_mad_i64_i32 v[150:151], s[18:19], v150, s14, v[10:11]
	v_mad_i64_i32 v[152:153], s[18:19], v152, s14, v[10:11]
	v_mad_i64_i32 v[154:155], s[18:19], v154, s14, v[10:11]
	v_mad_i64_i32 v[156:157], s[18:19], v156, s14, v[10:11]
	v_mad_i64_i32 v[158:159], s[18:19], v158, s14, v[10:11]
	v_mad_i64_i32 v[160:161], s[18:19], v160, s14, v[10:11]
	v_mad_i64_i32 v[162:163], s[18:19], v162, s14, v[10:11]
; #define LAS __attribute__((address_space(3)))
; __device__ __forceinline__ unsigned cvt_pk_bf16(float lo, float hi) { unsigned r; asm volatile("v_cvt_pk_bf16_f32 %0, %1, %2" : "=v"(r) : "v"(lo), "v"(hi)); return r; }
; #define LDS_WAIT() asm volatile("s_waitcnt lgkmcnt(0)" ::: "memory")
; __device__ __forceinline__ void p0_transpose_item(const float* W, int N, bf16_t* WT, int ldt, int k0, int n0, int nrow0, int kcol0, LAS float* scr, int lane) {
; #pragma unroll 8
;     for (int i = 0; i < 32; ++i) { const int kk = 2 * i + (lane >> 5); scr[kk * 33 + (lane & 31)] = W[(size_t)(k0 + kk) * N + n0 + (lane & 31)]; }
;     LDS_WAIT(); asm volatile("" ::: "memory");
;     const int c = lane & 7;
; #pragma unroll
;     for (int j = 0; j < 4; ++j) { const int n = (lane >> 3) + 8 * j; const LAS float* s = scr + (8 * c) * 33 + n;
;         u32x4 o; o.x = cvt_pk_bf16(s[0 * 33], s[1 * 33]); o.y = cvt_pk_bf16(s[2 * 33], s[3 * 33]); o.z = cvt_pk_bf16(s[4 * 33], s[5 * 33]); o.w = cvt_pk_bf16(s[6 * 33], s[7 * 33]);
;         *(u32x4*)(WT + (size_t)(nrow0 + n) * ldt + kcol0 + k0 + 8 * c) = o; }
;     LDS_WAIT(); asm volatile("" ::: "memory");
; }
; __device__ __forceinline__ void p0_prologue(const Frame& F) {
;     ...
;                 for (int it = first; it < nitems; it += NGW) { const int kb = it / nblk, nbk = it % nblk, n0 = nbk * 32;
;                     const int nrow0 = (jb == 0 && n0 >= 3392) ? n0 + 192 : n0;
;                     p0_transpose_item(W, J.N, WT, J.ldt, kb * 64, n0, nrow0, J.kcol0, scr, F.lane); }
	v_mad_i64_i32 v[164:165], s[18:19], v164, s14, v[10:11]
	v_mad_i64_i32 v[166:167], s[18:19], v166, s14, v[10:11]
	v_mad_i64_i32 v[168:169], s[18:19], v168, s14, v[10:11]
	v_mad_i64_i32 v[170:171], s[18:19], v170, s14, v[10:11]
	global_load_dword v188, v[140:141], off
	global_load_dword v189, v[142:143], off
	global_load_dword v190, v[144:145], off
	global_load_dword v191, v[146:147], off
	global_load_dword v192, v[148:149], off
	global_load_dword v193, v[150:151], off
	global_load_dword v194, v[152:153], off
	global_load_dword v195, v[154:155], off
	global_load_dword v196, v[156:157], off
	global_load_dword v197, v[158:159], off
	global_load_dword v198, v[160:161], off
	global_load_dword v199, v[162:163], off
	global_load_dword v200, v[164:165], off
	global_load_dword v201, v[166:167], off
	global_load_dword v202, v[168:169], off
	global_load_dword v203, v[170:171], off
	s_add_i32 s16, s16, 16
	s_add_i32 s17, s17, 16
	s_add_i32 s9, s9, -16
	v_mad_u64_u32 v[140:141], s[18:19], v173, s13, v[6:7]
	s_cmp_lg_u32 s9, 0
	v_mad_u64_u32 v[142:143], s[18:19], v172, s13, v[6:7]
	v_mad_u64_u32 v[144:145], s[18:19], v175, s13, v[6:7]
	v_mad_u64_u32 v[146:147], s[18:19], v174, s13, v[6:7]
	v_mad_u64_u32 v[148:149], s[18:19], v177, s13, v[6:7]
	v_mad_u64_u32 v[150:151], s[18:19], v176, s13, v[6:7]
	v_mad_u64_u32 v[152:153], s[18:19], v179, s13, v[6:7]
	v_mad_u64_u32 v[154:155], s[18:19], v178, s13, v[6:7]
	v_mad_u64_u32 v[156:157], s[18:19], v181, s13, v[6:7]
	v_mad_u64_u32 v[158:159], s[18:19], v180, s13, v[6:7]
	v_mad_u64_u32 v[160:161], s[18:19], v183, s13, v[6:7]
	v_mad_u64_u32 v[162:163], s[18:19], v182, s13, v[6:7]
	v_mad_u64_u32 v[164:165], s[18:19], v185, s13, v[6:7]
	v_mad_u64_u32 v[166:167], s[18:19], v184, s13, v[6:7]
	v_mad_u64_u32 v[168:169], s[18:19], v187, s13, v[6:7]
	v_mad_u64_u32 v[170:171], s[18:19], v186, s13, v[6:7]
	s_waitcnt vmcnt(31)
	ds_write_b32 v18, v66
	s_waitcnt vmcnt(30)
	ds_write_b32 v20, v67
	s_waitcnt vmcnt(29)
	ds_write_b32 v22, v68
	s_waitcnt vmcnt(28)
	ds_write_b32 v24, v69
	s_waitcnt vmcnt(27)
	ds_write_b32 v26, v70
	s_waitcnt vmcnt(26)
	ds_write_b32 v28, v71
	s_waitcnt vmcnt(25)
	ds_write_b32 v30, v72
	s_waitcnt vmcnt(24)
	ds_write_b32 v32, v73
	s_waitcnt vmcnt(23)
	ds_write_b32 v34, v74
	s_waitcnt vmcnt(22)
	ds_write_b32 v36, v75
	s_waitcnt vmcnt(21)
	ds_write_b32 v38, v76
	s_waitcnt vmcnt(20)
	ds_write_b32 v40, v77
	s_waitcnt vmcnt(19)
	ds_write_b32 v42, v78
	s_waitcnt vmcnt(18)
	ds_write_b32 v44, v79
	s_waitcnt vmcnt(17)
	ds_write_b32 v46, v80
	s_waitcnt vmcnt(16)
	ds_write_b32 v48, v81
	s_waitcnt vmcnt(15)
	ds_write_b32 v140, v188
	s_waitcnt vmcnt(14)
	ds_write_b32 v142, v189
	s_waitcnt vmcnt(13)
	ds_write_b32 v144, v190
	s_waitcnt vmcnt(12)
	ds_write_b32 v146, v191
	s_waitcnt vmcnt(11)
	ds_write_b32 v148, v192
	s_waitcnt vmcnt(10)
	ds_write_b32 v150, v193
	s_waitcnt vmcnt(9)
	ds_write_b32 v152, v194
	s_waitcnt vmcnt(8)
	ds_write_b32 v154, v195
	s_waitcnt vmcnt(7)
	ds_write_b32 v156, v196
	s_waitcnt vmcnt(6)
	ds_write_b32 v158, v197
	s_waitcnt vmcnt(5)
	ds_write_b32 v160, v198
	s_waitcnt vmcnt(4)
	ds_write_b32 v162, v199
	s_waitcnt vmcnt(3)
	ds_write_b32 v164, v200
	s_waitcnt vmcnt(2)
	ds_write_b32 v166, v201
	s_waitcnt vmcnt(1)
	ds_write_b32 v168, v202
	s_waitcnt vmcnt(0)
	ds_write_b32 v170, v203
	s_waitcnt lgkmcnt(0)
	ds_read2_b32 v[10:11], v7 offset1:33
	v_or_b32_e32 v24, s6, v3
	s_waitcnt lgkmcnt(0)
	v_cvt_pk_bf16_f32 v18, v10, v11
	ds_read2_b32 v[10:11], v7 offset0:66 offset1:99
	s_ashr_i32 s9, s8, 31
	v_mul_lo_u32 v24, v24, s15
	s_waitcnt lgkmcnt(0)
	v_cvt_pk_bf16_f32 v19, v10, v11
	ds_read2_b32 v[10:11], v7 offset0:132 offset1:165
	v_lshl_add_u64 v[22:23], s[8:9], 1, v[8:9]
	v_ashrrev_i32_e32 v25, 31, v24
	s_waitcnt lgkmcnt(0)
	v_cvt_pk_bf16_f32 v20, v10, v11
	ds_read2_b32 v[10:11], v7 offset0:198 offset1:231
	v_lshl_add_u64 v[24:25], v[22:23], 0, v[24:25]
	s_waitcnt lgkmcnt(0)
	v_cvt_pk_bf16_f32 v21, v10, v11
	ds_read2_b32 v[10:11], v7 offset0:8 offset1:41
	global_store_dwordx4 v[24:25], v[18:21], off
	v_or_b32_e32 v24, s6, v13
	v_mul_lo_u32 v24, v24, s15
	s_waitcnt lgkmcnt(0)
	v_cvt_pk_bf16_f32 v18, v10, v11
	ds_read2_b32 v[10:11], v7 offset0:74 offset1:107
	s_waitcnt lgkmcnt(0)
	v_cvt_pk_bf16_f32 v19, v10, v11
	ds_read2_b32 v[10:11], v7 offset0:140 offset1:173
	v_ashrrev_i32_e32 v25, 31, v24
	s_waitcnt lgkmcnt(0)
	v_cvt_pk_bf16_f32 v20, v10, v11
	ds_read2_b32 v[10:11], v7 offset0:206 offset1:239
	v_lshl_add_u64 v[24:25], v[22:23], 0, v[24:25]
	s_waitcnt lgkmcnt(0)
	v_cvt_pk_bf16_f32 v21, v10, v11
	ds_read2_b32 v[10:11], v7 offset0:16 offset1:49
	global_store_dwordx4 v[24:25], v[18:21], off
	v_or_b32_e32 v24, s6, v16
	v_mul_lo_u32 v24, v24, s15
	s_waitcnt lgkmcnt(0)
	v_cvt_pk_bf16_f32 v18, v10, v11
	ds_read2_b32 v[10:11], v7 offset0:82 offset1:115
	s_waitcnt lgkmcnt(0)
	v_cvt_pk_bf16_f32 v19, v10, v11
	ds_read2_b32 v[10:11], v7 offset0:148 offset1:181
	v_ashrrev_i32_e32 v25, 31, v24
	s_waitcnt lgkmcnt(0)
	v_cvt_pk_bf16_f32 v20, v10, v11
	ds_read2_b32 v[10:11], v7 offset0:214 offset1:247
	s_waitcnt lgkmcnt(0)
	v_cvt_pk_bf16_f32 v21, v10, v11
	v_lshl_add_u64 v[24:25], v[22:23], 0, v[24:25]
	global_store_dwordx4 v[24:25], v[18:21], off
	ds_read2_b32 v[10:11], v7 offset0:24 offset1:57
	s_add_i32 s12, s12, s3
	v_or_b32_e32 v21, s6, v17
	v_mul_lo_u32 v24, v21, s15
	s_waitcnt lgkmcnt(0)
	v_cvt_pk_bf16_f32 v18, v10, v11
	ds_read2_b32 v[10:11], v7 offset0:90 offset1:123
	v_ashrrev_i32_e32 v25, 31, v24
	s_waitcnt lgkmcnt(0)
	v_cvt_pk_bf16_f32 v19, v10, v11
	ds_read2_b32 v[10:11], v7 offset0:156 offset1:189
	v_lshl_add_u64 v[22:23], v[22:23], 0, v[24:25]
	s_waitcnt lgkmcnt(0)
	v_cvt_pk_bf16_f32 v20, v10, v11
	ds_read2_b32 v[10:11], v7 offset0:222 offset1:255
	s_waitcnt lgkmcnt(0)
	v_cvt_pk_bf16_f32 v21, v10, v11
	global_store_dwordx4 v[22:23], v[18:21], off
	s_waitcnt lgkmcnt(0)
	s_cmpk_lt_i32 s12, 0x480
	s_cbranch_scc1 .LBB0_79
